# attention: two wave halves staggered one segment apart (2 barriers per tile, K/V DMA issue split per half), QK/PV LDS prefetch
# baseline (speedup 1.0000x reference)
.LBB0_998:
	s_or_b64 exec, exec, s[12:13]
	s_waitcnt vmcnt(0)
	v_mov_b32_e32 v24, v161
	v_mov_b32_e32 v25, v161
	v_mov_b32_e32 v26, v161
	v_mov_b32_e32 v27, v161
	s_lshl_b32 s9, s26, 12
	v_mov_b64_e32 v[30:31], v[26:27]
	v_mov_b64_e32 v[38:39], v[26:27]
	v_mov_b64_e32 v[42:43], v[26:27]
	v_mov_b64_e32 v[46:47], v[26:27]
	v_mov_b64_e32 v[50:51], v[26:27]
	v_mov_b64_e32 v[54:55], v[26:27]
	v_mov_b64_e32 v[58:59], v[26:27]
	v_mov_b64_e32 v[62:63], v[26:27]
	v_mov_b64_e32 v[34:35], v[26:27]
	s_waitcnt vmcnt(0)
	v_mov_b64_e32 v[16:17], v[24:25]
	v_mov_b64_e32 v[20:21], v[24:25]
	v_mov_b64_e32 v[8:9], v[24:25]
	v_mov_b64_e32 v[12:13], v[24:25]
	v_mov_b64_e32 v[0:1], v[24:25]
	v_mov_b64_e32 v[4:5], v[24:25]
	v_ashrrev_i32_e32 v153, 31, v152
	v_ashrrev_i32_e32 v151, 31, v150
	v_mov_b32_e32 v159, v161
	v_mov_b32_e32 v173, v161
	v_mov_b32_e32 v175, v161
	s_add_i32 s13, s9, 0xffffff40
	v_mov_b32_e32 v177, v161
	v_mov_b32_e32 v179, v161
	s_add_i32 s26, s27, 1
	s_add_i32 s27, s8, 64
	s_mov_b32 s29, 0
	v_mov_b32_e32 v154, 0
	v_mov_b32_e32 v203, 0xf149f2ca
	v_mov_b64_e32 v[28:29], v[24:25]
	v_mov_b64_e32 v[36:37], v[24:25]
	v_mov_b64_e32 v[40:41], v[24:25]
	v_mov_b64_e32 v[44:45], v[24:25]
	v_mov_b64_e32 v[48:49], v[24:25]
	v_mov_b64_e32 v[52:53], v[24:25]
	v_mov_b64_e32 v[56:57], v[24:25]
	v_mov_b64_e32 v[60:61], v[24:25]
	v_mov_b32_e32 v162, 0xf149f2ca
	v_mov_b32_e32 v156, 0
	v_mov_b64_e32 v[32:33], v[24:25]
	v_mov_b64_e32 v[18:19], v[26:27]
	v_mov_b64_e32 v[22:23], v[26:27]
	v_mov_b64_e32 v[10:11], v[26:27]
	v_mov_b64_e32 v[14:15], v[26:27]
	v_mov_b64_e32 v[2:3], v[26:27]
	v_mov_b64_e32 v[6:7], v[26:27]
	s_waitcnt lgkmcnt(0)
	s_barrier
	v_readfirstlane_b32 s30, v190
	s_cmp_lt_u32 s30, 0x100
	s_cbranch_scc1 .LBB0_999
	s_cmp_lt_u32 s29, 3
	s_cselect_b32 s8, s27, s13
	s_mov_b32 s12, 0xa800
	s_mul_i32 s10, s8, 0xc00
	s_mul_hi_i32 s11, s8, 0xc00
	s_add_u32 s10, s16, s10
	s_addc_u32 s11, s17, s11
	v_add_u32_e32 v112, s12, v181
	v_add_u32_e32 v113, 0x2000, v112
	v_readfirstlane_b32 s30, v112
	v_lshl_add_u64 v[114:115], s[10:11], 0, v[158:159]
	s_mov_b32 m0, s30
	v_readfirstlane_b32 s30, v113
	global_load_lds_dwordx4 v[114:115], off
	v_lshl_add_u64 v[114:115], s[10:11], 0, v[172:173]
	s_mov_b32 m0, s30
	v_add_u32_e32 v113, 0x4000, v112
	global_load_lds_dwordx4 v[114:115], off
	v_lshl_add_u64 v[114:115], s[10:11], 0, v[174:175]
	v_readfirstlane_b32 s30, v113
	s_mov_b32 m0, s30
	s_nop 0
	global_load_lds_dwordx4 v[114:115], off
	s_barrier
.LBB0_999:
	s_add_i32 s28, s29, 1
	s_cmp_lt_u32 s29, 3
	s_cselect_b32 s8, s27, s13
	s_bitcmp1_b32 s28, 0
	s_cselect_b32 s12, 0xa800, 0
	v_readfirstlane_b32 s30, v190
	s_cmp_lt_u32 s30, 0x100
	s_cbranch_scc0 .Lat_topY
	s_mul_i32 s10, s8, 0xc00
	s_mul_hi_i32 s11, s8, 0xc00
	s_add_u32 s10, s16, s10
	s_addc_u32 s11, s17, s11
	v_add_u32_e32 v112, s12, v181
	v_add_u32_e32 v113, 0x2000, v112
	v_readfirstlane_b32 s30, v112
	v_lshl_add_u64 v[114:115], s[10:11], 0, v[158:159]
	s_mov_b32 m0, s30
	v_readfirstlane_b32 s30, v113
	global_load_lds_dwordx4 v[114:115], off
	v_lshl_add_u64 v[114:115], s[10:11], 0, v[172:173]
	s_mov_b32 m0, s30
	v_add_u32_e32 v113, 0x4000, v112
	global_load_lds_dwordx4 v[114:115], off
	v_lshl_add_u64 v[114:115], s[10:11], 0, v[174:175]
	v_readfirstlane_b32 s30, v113
	s_mov_b32 m0, s30
	s_nop 0
	global_load_lds_dwordx4 v[114:115], off
	s_branch .Lat_qk
.Lat_topY:
	s_ashr_i32 s9, s8, 31
	s_lshl_b64 s[8:9], s[8:9], 1
	s_add_u32 s8, s18, s8
	s_addc_u32 s9, s19, s9
	v_add_u32_e32 v112, s12, v181
	s_and_saveexec_b64 s[10:11], s[2:3]
	s_cbranch_execz .Lat_vskip1_0
	v_add_u32_e32 v113, 0x6000, v112
	v_lshl_add_u64 v[114:115], s[8:9], 0, v[176:177]
	v_readfirstlane_b32 s30, v113
	s_mov_b32 m0, s30
	s_nop 0
	global_load_lds_dwordx4 v[114:115], off
.Lat_vskip1_0:
	s_or_b64 exec, exec, s[10:11]
	s_and_saveexec_b64 s[10:11], s[4:5]
	s_cbranch_execz .Lat_vskip1_1
	v_add_u32_e32 v113, 0x8000, v112
	v_lshl_add_u64 v[114:115], s[8:9], 0, v[178:179]
	v_readfirstlane_b32 s30, v113
	s_mov_b32 m0, s30
	s_nop 0
	global_load_lds_dwordx4 v[114:115], off
.Lat_vskip1_1:
	s_or_b64 exec, exec, s[10:11]
	s_and_saveexec_b64 s[10:11], s[6:7]
	s_cbranch_execz .Lat_vskip1_2
	v_add_u32_e32 v113, 0xa000, v112
	v_lshl_add_u64 v[114:115], s[8:9], 0, v[160:161]
	v_readfirstlane_b32 s30, v113
	s_mov_b32 m0, s30
	s_nop 0
	global_load_lds_dwordx4 v[114:115], off

.Lat_qk:
	s_bitcmp1_b32 s29, 0
	s_cselect_b32 s8, 0xa800, 0
	s_setprio 0
	v_add_u32_e32 v116, s8, v198
	ds_read_b128 v[116:119], v116
	v_add_u32_e32 v124, s8, v199
	ds_read_b128 v[124:127], v124
	v_add_u32_e32 v128, s8, v200
	ds_read_b128 v[128:131], v128
	v_add_u32_e32 v136, s8, v201
	ds_read_b128 v[136:139], v136
	v_add_u32_e32 v132, s8, v225
	ds_read_b128 v[132:135], v132
	v_add_u32_e32 v140, s8, v226
	ds_read_b128 v[140:143], v140
	s_waitcnt lgkmcnt(5)
	v_mfma_f32_16x16x32_bf16 v[112:115], v[116:119], v[104:107], 0
	v_mfma_f32_16x16x32_bf16 v[120:123], v[116:119], v[108:111], 0
	v_add_u32_e32 v204, s8, v234
	ds_read_b128 v[204:207], v204
	s_waitcnt lgkmcnt(5)
	v_mfma_f32_16x16x32_bf16 v[112:115], v[124:127], v[96:99], v[112:115]
	v_mfma_f32_16x16x32_bf16 v[120:123], v[124:127], v[100:103], v[120:123]
	v_add_u32_e32 v208, s8, v235
	ds_read_b128 v[208:211], v208
	s_waitcnt lgkmcnt(5)
	v_mfma_f32_16x16x32_bf16 v[112:115], v[128:131], v[88:91], v[112:115]
	v_mfma_f32_16x16x32_bf16 v[120:123], v[128:131], v[92:95], v[120:123]
	v_add_u32_e32 v128, s8, v236
	ds_read_b128 v[128:131], v128
	s_waitcnt lgkmcnt(5)
	v_mfma_f32_16x16x32_bf16 v[112:115], v[136:139], v[80:83], v[112:115]
	v_mfma_f32_16x16x32_bf16 v[120:123], v[136:139], v[84:87], v[120:123]
	v_add_u32_e32 v136, s8, v237
	ds_read_b128 v[136:139], v136
	s_waitcnt lgkmcnt(5)
	v_mfma_f32_16x16x32_bf16 v[112:115], v[132:135], v[72:75], v[112:115]
	v_mfma_f32_16x16x32_bf16 v[120:123], v[132:135], v[76:79], v[120:123]
	v_add_u32_e32 v132, s8, v238
	ds_read_b128 v[132:135], v132
	s_waitcnt lgkmcnt(5)
	v_mfma_f32_16x16x32_bf16 v[112:115], v[140:143], v[64:67], v[112:115]
	v_mfma_f32_16x16x32_bf16 v[120:123], v[140:143], v[68:71], v[120:123]
	v_add_u32_e32 v140, s8, v239
	ds_read_b128 v[140:143], v140
	s_waitcnt lgkmcnt(5)
	v_mfma_f32_16x16x32_bf16 v[116:119], v[204:207], v[104:107], 0
	v_mfma_f32_16x16x32_bf16 v[124:127], v[204:207], v[108:111], 0
	v_add_u32_e32 v204, s8, v240
	ds_read_b128 v[204:207], v204
	s_waitcnt lgkmcnt(5)
	v_mfma_f32_16x16x32_bf16 v[116:119], v[208:211], v[96:99], v[116:119]
	v_mfma_f32_16x16x32_bf16 v[124:127], v[208:211], v[100:103], v[124:127]
	v_add_u32_e32 v208, s8, v241
	ds_read_b128 v[208:211], v208
	s_waitcnt lgkmcnt(5)
	v_mfma_f32_16x16x32_bf16 v[116:119], v[128:131], v[88:91], v[116:119]
	v_mfma_f32_16x16x32_bf16 v[124:127], v[128:131], v[92:95], v[124:127]
	s_waitcnt lgkmcnt(4)
	v_mfma_f32_16x16x32_bf16 v[116:119], v[136:139], v[80:83], v[116:119]
	v_mfma_f32_16x16x32_bf16 v[124:127], v[136:139], v[84:87], v[124:127]
	s_waitcnt lgkmcnt(3)
	v_mfma_f32_16x16x32_bf16 v[116:119], v[132:135], v[72:75], v[116:119]
	v_mfma_f32_16x16x32_bf16 v[124:127], v[132:135], v[76:79], v[124:127]
	v_add_u32_e32 v132, s8, v242
	ds_read_b128 v[132:135], v132
	s_waitcnt lgkmcnt(3)
	v_mfma_f32_16x16x32_bf16 v[116:119], v[140:143], v[64:67], v[116:119]
	v_mfma_f32_16x16x32_bf16 v[124:127], v[140:143], v[68:71], v[124:127]
	v_add_u32_e32 v140, s8, v243
	ds_read_b128 v[140:143], v140
	s_waitcnt lgkmcnt(3)
	v_mfma_f32_16x16x32_bf16 v[136:139], v[204:207], v[104:107], 0
	v_mfma_f32_16x16x32_bf16 v[128:131], v[204:207], v[108:111], 0
	v_add_u32_e32 v204, s8, v244
	ds_read_b128 v[204:207], v204
	s_waitcnt lgkmcnt(3)
	v_mfma_f32_16x16x32_bf16 v[136:139], v[208:211], v[96:99], v[136:139]
	v_mfma_f32_16x16x32_bf16 v[128:131], v[208:211], v[100:103], v[128:131]
	v_add_u32_e32 v208, s8, v245
	ds_read_b128 v[208:211], v208
	s_waitcnt lgkmcnt(3)
	v_mfma_f32_16x16x32_bf16 v[136:139], v[132:135], v[88:91], v[136:139]
	v_mfma_f32_16x16x32_bf16 v[128:131], v[132:135], v[92:95], v[128:131]
	s_waitcnt lgkmcnt(2)
	v_mfma_f32_16x16x32_bf16 v[136:139], v[140:143], v[80:83], v[136:139]
	v_mfma_f32_16x16x32_bf16 v[128:131], v[140:143], v[84:87], v[128:131]
	s_waitcnt lgkmcnt(1)
	v_mfma_f32_16x16x32_bf16 v[136:139], v[204:207], v[72:75], v[136:139]
	v_mfma_f32_16x16x32_bf16 v[128:131], v[204:207], v[76:79], v[128:131]
	v_add_u32_e32 v204, s8, v246
	ds_read_b128 v[204:207], v204
	s_waitcnt lgkmcnt(1)
	v_mfma_f32_16x16x32_bf16 v[136:139], v[208:211], v[64:67], v[136:139]
	v_mfma_f32_16x16x32_bf16 v[128:131], v[208:211], v[68:71], v[128:131]
	v_add_u32_e32 v208, s8, v247
	ds_read_b128 v[208:211], v208
	s_waitcnt lgkmcnt(1)
	v_mfma_f32_16x16x32_bf16 v[140:143], v[204:207], v[104:107], 0
	v_mfma_f32_16x16x32_bf16 v[132:135], v[204:207], v[108:111], 0
	v_add_u32_e32 v204, s8, v248
	ds_read_b128 v[204:207], v204
	s_waitcnt lgkmcnt(1)
	v_mfma_f32_16x16x32_bf16 v[140:143], v[208:211], v[96:99], v[140:143]
	v_mfma_f32_16x16x32_bf16 v[132:135], v[208:211], v[100:103], v[132:135]
	v_add_u32_e32 v208, s8, v249
	ds_read_b128 v[208:211], v208
	s_waitcnt lgkmcnt(1)
	v_mfma_f32_16x16x32_bf16 v[140:143], v[204:207], v[88:91], v[140:143]
	v_mfma_f32_16x16x32_bf16 v[132:135], v[204:207], v[92:95], v[132:135]
	v_add_u32_e32 v204, s8, v250
	ds_read_b128 v[204:207], v204
	s_waitcnt lgkmcnt(1)
	v_mfma_f32_16x16x32_bf16 v[140:143], v[208:211], v[80:83], v[140:143]
	v_mfma_f32_16x16x32_bf16 v[132:135], v[208:211], v[84:87], v[132:135]
	v_add_u32_e32 v208, s8, v251
	ds_read_b128 v[208:211], v208
	s_waitcnt lgkmcnt(1)
	v_mfma_f32_16x16x32_bf16 v[140:143], v[204:207], v[72:75], v[140:143]
	v_mfma_f32_16x16x32_bf16 v[132:135], v[204:207], v[76:79], v[132:135]
	s_waitcnt lgkmcnt(0)
	v_mfma_f32_16x16x32_bf16 v[140:143], v[208:211], v[64:67], v[140:143]
	v_mfma_f32_16x16x32_bf16 v[132:135], v[208:211], v[68:71], v[132:135]
	s_nop 3
	v_readfirstlane_b32 s30, v190
	s_cmp_lt_u32 s30, 0x100
	s_cbranch_scc0 .Lat_mY
	s_waitcnt vmcnt(3)
	s_barrier
	s_cmp_lt_u32 s29, 3
	s_cselect_b32 s8, s27, s13
	s_ashr_i32 s9, s8, 31
	s_lshl_b64 s[8:9], s[8:9], 1
	s_add_u32 s8, s18, s8
	s_addc_u32 s9, s19, s9
	v_add_u32_e32 v204, s12, v181
	s_and_saveexec_b64 s[10:11], s[2:3]
	s_cbranch_execz .Lat_vskip2_0
	v_add_u32_e32 v205, 0x6000, v204
	v_lshl_add_u64 v[206:207], s[8:9], 0, v[176:177]
	v_readfirstlane_b32 s30, v205
	s_mov_b32 m0, s30
	s_nop 0
	global_load_lds_dwordx4 v[206:207], off
.Lat_vskip2_0:
	s_or_b64 exec, exec, s[10:11]
	s_and_saveexec_b64 s[10:11], s[4:5]
	s_cbranch_execz .Lat_vskip2_1
	v_add_u32_e32 v205, 0x8000, v204
	v_lshl_add_u64 v[206:207], s[8:9], 0, v[178:179]
	v_readfirstlane_b32 s30, v205
	s_mov_b32 m0, s30
	s_nop 0
	global_load_lds_dwordx4 v[206:207], off
.Lat_vskip2_1:
	s_or_b64 exec, exec, s[10:11]
	s_and_saveexec_b64 s[10:11], s[6:7]
	s_cbranch_execz .Lat_vskip2_2
	v_add_u32_e32 v205, 0xa000, v204
	v_lshl_add_u64 v[206:207], s[8:9], 0, v[160:161]
	v_readfirstlane_b32 s30, v205
	s_mov_b32 m0, s30
	s_nop 0
	global_load_lds_dwordx4 v[206:207], off
.Lat_vskip2_2:
	s_or_b64 exec, exec, s[10:11]
	s_branch .Lat_sm
.Lat_mY:
	s_waitcnt vmcnt(2)
	s_barrier
	s_cmp_eq_u32 s26, s28
	s_cbranch_scc1 .Lat_sm
	s_add_i32 s8, s27, 64
	s_add_i32 s9, s13, 64
	s_cmp_lt_u32 s28, 3
	s_cselect_b32 s8, s8, s9
	s_bitcmp1_b32 s29, 0
	s_cselect_b32 s9, 0xa800, 0
	s_mul_i32 s10, s8, 0xc00
	s_mul_hi_i32 s11, s8, 0xc00
	s_add_u32 s10, s16, s10
	s_addc_u32 s11, s17, s11
	v_add_u32_e32 v204, s9, v181
	v_add_u32_e32 v205, 0x2000, v204
	v_readfirstlane_b32 s30, v204
	v_lshl_add_u64 v[206:207], s[10:11], 0, v[158:159]
	s_mov_b32 m0, s30
	v_readfirstlane_b32 s30, v205
	global_load_lds_dwordx4 v[206:207], off
	v_lshl_add_u64 v[206:207], s[10:11], 0, v[172:173]
	s_mov_b32 m0, s30
	v_add_u32_e32 v205, 0x4000, v204
	global_load_lds_dwordx4 v[206:207], off
	v_lshl_add_u64 v[206:207], s[10:11], 0, v[174:175]
	v_readfirstlane_b32 s30, v205
	s_mov_b32 m0, s30
	s_nop 0
	global_load_lds_dwordx4 v[206:207], off
.Lat_sm:
	s_setprio 1
	v_max_f32_e32 v157, v112, v112
	v_max_f32_e32 v195, v114, v114
	v_max_f32_e32 v155, v113, v113
	v_max_f32_e32 v155, v157, v155
	v_max_f32_e32 v157, v115, v115
	v_max_f32_e32 v157, v195, v157
	v_max_f32_e32 v195, v119, v119
	v_max_f32_e32 v204, v118, v118
	v_max_f32_e32 v195, v204, v195
	v_max3_f32 v195, v116, v117, v195
	v_max3_f32 v155, v155, v157, v195
	v_max_f32_e32 v157, v139, v139
	v_max_f32_e32 v195, v138, v138
	v_max_f32_e32 v157, v195, v157
	v_max_f32_e32 v195, v143, v143
	v_max_f32_e32 v204, v142, v142
	v_max_f32_e32 v195, v204, v195
	v_max3_f32 v157, v136, v137, v157
	v_max3_f32 v195, v140, v141, v195
	v_max3_f32 v155, v155, v157, v195
	v_sub_f32_e32 v157, v155, v162
	v_cmp_ge_f32_e32 vcc, s89, v157
	s_cmp_eq_u64 vcc, exec
	s_cbranch_scc1 .LBB0_1005
	v_and_b32_e32 v195, 64, v227
	v_xor_b32_e32 v157, 16, v227
	v_add_u32_e32 v195, 64, v195
	v_cmp_lt_i32_e32 vcc, v157, v195
	s_nop 1
	v_cndmask_b32_e32 v157, v227, v157, vcc
	v_lshlrev_b32_e32 v157, 2, v157
	ds_bpermute_b32 v157, v157, v155
	v_max_f32_e32 v155, v155, v155
	s_waitcnt lgkmcnt(0)
	v_max_f32_e32 v157, v157, v157
	v_max_f32_e32 v155, v155, v157
	v_xor_b32_e32 v157, 32, v227
	v_cmp_lt_i32_e32 vcc, v157, v195
	s_nop 1
	v_cndmask_b32_e32 v157, v227, v157, vcc
	v_lshlrev_b32_e32 v157, 2, v157
	ds_bpermute_b32 v157, v157, v155
	s_waitcnt lgkmcnt(0)
	v_max3_f32 v155, v162, v155, v157
	v_sub_f32_e32 v157, v162, v155
	v_mul_f32_e32 v157, 0x3dd53b94, v157
	v_exp_f32_e32 v162, v157
	s_nop 0
	v_mul_f32_e32 v156, v156, v162
	v_pk_mul_f32 v[62:63], v[62:63], v[162:163] op_sel_hi:[1,0]
	v_pk_mul_f32 v[60:61], v[60:61], v[162:163] op_sel_hi:[1,0]
	v_pk_mul_f32 v[54:55], v[54:55], v[162:163] op_sel_hi:[1,0]
	v_pk_mul_f32 v[52:53], v[52:53], v[162:163] op_sel_hi:[1,0]
	v_pk_mul_f32 v[46:47], v[46:47], v[162:163] op_sel_hi:[1,0]
	v_pk_mul_f32 v[44:45], v[44:45], v[162:163] op_sel_hi:[1,0]
	v_pk_mul_f32 v[38:39], v[38:39], v[162:163] op_sel_hi:[1,0]
	v_pk_mul_f32 v[36:37], v[36:37], v[162:163] op_sel_hi:[1,0]
	v_pk_mul_f32 v[26:27], v[26:27], v[162:163] op_sel_hi:[1,0]
	v_pk_mul_f32 v[24:25], v[24:25], v[162:163] op_sel_hi:[1,0]
	v_pk_mul_f32 v[18:19], v[18:19], v[162:163] op_sel_hi:[1,0]
	v_pk_mul_f32 v[16:17], v[16:17], v[162:163] op_sel_hi:[1,0]
	v_pk_mul_f32 v[10:11], v[10:11], v[162:163] op_sel_hi:[1,0]
	v_pk_mul_f32 v[8:9], v[8:9], v[162:163] op_sel_hi:[1,0]
	v_pk_mul_f32 v[2:3], v[2:3], v[162:163] op_sel_hi:[1,0]
	v_pk_mul_f32 v[0:1], v[0:1], v[162:163] op_sel_hi:[1,0]
	v_mov_b32_e32 v162, v155

.LBB0_1007:
	v_add_f32_e32 v155, 0, v155
	v_add_f32_e32 v155, v204, v155
	v_add_f32_e32 v155, v205, v155
	v_add_f32_e32 v155, v206, v155
	v_add_f32_e32 v155, v207, v155
	v_add_f32_e32 v155, v208, v155
	v_add_f32_e32 v155, v230, v155
	v_add_f32_e32 v155, v195, v155
	v_add_f32_e32 v136, v136, v155
	v_add_f32_e32 v136, v137, v136
	v_add_f32_e32 v136, v138, v136
	v_mul_f32_e32 v155, 0xbdd53b94, v203
	v_add_f32_e32 v136, v139, v136
	v_fmamk_f32 v120, v120, 0x3dd53b94, v155
	v_add_f32_e32 v136, v140, v136
	v_exp_f32_e32 v120, v120
	v_fmamk_f32 v121, v121, 0x3dd53b94, v155
	v_add_f32_e32 v136, v141, v136
	v_exp_f32_e32 v121, v121
	v_fmamk_f32 v122, v122, 0x3dd53b94, v155
	v_add_f32_e32 v136, v142, v136
	v_exp_f32_e32 v122, v122
	v_fmamk_f32 v123, v123, 0x3dd53b94, v155
	v_add_f32_e32 v136, v143, v136
	v_exp_f32_e32 v123, v123
	v_fmamk_f32 v124, v124, 0x3dd53b94, v155
	v_add_f32_e32 v156, v156, v136
	v_add_f32_e32 v136, 0, v120
	v_exp_f32_e32 v137, v124
	v_add_f32_e32 v136, v121, v136
	v_add_f32_e32 v136, v122, v136
	v_add_f32_e32 v136, v123, v136
	v_fmamk_f32 v125, v125, 0x3dd53b94, v155
	v_add_f32_e32 v124, v137, v136
	v_exp_f32_e32 v136, v125
	v_fmamk_f32 v125, v126, 0x3dd53b94, v155
	v_exp_f32_e32 v138, v125
	v_fmamk_f32 v125, v127, 0x3dd53b94, v155
	v_exp_f32_e32 v127, v125
	v_fmamk_f32 v125, v128, 0x3dd53b94, v155
	v_exp_f32_e32 v128, v125
	v_fmamk_f32 v125, v129, 0x3dd53b94, v155
	v_add_f32_e32 v124, v136, v124
	v_exp_f32_e32 v129, v125
	v_fmamk_f32 v125, v130, 0x3dd53b94, v155
	v_add_f32_e32 v124, v138, v124
	v_exp_f32_e32 v130, v125
	v_fmamk_f32 v125, v131, 0x3dd53b94, v155
	v_add_f32_e32 v124, v127, v124
	v_exp_f32_e32 v131, v125
	v_fmamk_f32 v125, v132, 0x3dd53b94, v155
	v_add_f32_e32 v124, v128, v124
	v_exp_f32_e32 v132, v125
	v_fmamk_f32 v125, v133, 0x3dd53b94, v155
	v_add_f32_e32 v124, v129, v124
	v_exp_f32_e32 v133, v125
	v_fmamk_f32 v125, v134, 0x3dd53b94, v155
	v_add_f32_e32 v124, v130, v124
	v_exp_f32_e32 v134, v125
	v_fmamk_f32 v125, v135, 0x3dd53b94, v155
	v_add_f32_e32 v124, v131, v124
	v_exp_f32_e32 v135, v125
	v_add_f32_e32 v124, v132, v124
	v_add_f32_e32 v124, v133, v124
	v_add_f32_e32 v124, v134, v124
	v_add_f32_e32 v124, v135, v124
	v_add_f32_e32 v154, v154, v124
	v_cvt_pk_bf16_f32 v124, v120, v121
	v_cvt_pk_bf16_f32 v125, v122, v123
	v_cvt_pk_bf16_f32 v126, v137, v136
	v_cvt_pk_bf16_f32 v127, v138, v127
	v_cvt_pk_bf16_f32 v120, v128, v129
	v_cvt_pk_bf16_f32 v121, v130, v131
	v_cvt_pk_bf16_f32 v122, v132, v133
	v_cvt_pk_bf16_f32 v123, v134, v135
	s_bitcmp1_b32 s29, 0
	s_cselect_b32 s8, 0xa800, 0
	v_add3_u32 v230, s8, v144, v202
	ds_read_b64 v[128:129], v230 offset:24576
	ds_read_b64 v[130:131], v230 offset:24608
	ds_read_b64 v[132:133], v230 offset:24640
	ds_read_b64 v[134:135], v230 offset:24672
	ds_read_b64 v[136:137], v230 offset:26880
	ds_read_b64 v[138:139], v230 offset:26912
	ds_read_b64 v[140:141], v230 offset:26944
	ds_read_b64 v[142:143], v230 offset:26976
	ds_read_b64 v[204:205], v230 offset:29184
	ds_read_b64 v[206:207], v230 offset:29216
	ds_read_b64 v[208:209], v230 offset:29248
	ds_read_b64 v[210:211], v230 offset:29280
	s_waitcnt lgkmcnt(10)
	v_mfma_f32_16x16x32_bf16 v[60:63], v[128:131], v[116:119], v[60:63]
	v_mfma_f32_16x16x32_bf16 v[56:59], v[128:131], v[124:127], v[56:59]
	ds_read_b64 v[128:129], v230 offset:31488
	ds_read_b64 v[130:131], v230 offset:31520
	s_waitcnt lgkmcnt(10)
	v_mfma_f32_16x16x32_bf16 v[60:63], v[132:135], v[112:115], v[60:63]
	v_mfma_f32_16x16x32_bf16 v[56:59], v[132:135], v[120:123], v[56:59]
	ds_read_b64 v[132:133], v230 offset:31552
	ds_read_b64 v[134:135], v230 offset:31584
	s_waitcnt lgkmcnt(10)
	v_mfma_f32_16x16x32_bf16 v[52:55], v[136:139], v[116:119], v[52:55]
	v_mfma_f32_16x16x32_bf16 v[48:51], v[136:139], v[124:127], v[48:51]
	ds_read_b64 v[136:137], v230 offset:33792
	ds_read_b64 v[138:139], v230 offset:33824
	s_waitcnt lgkmcnt(10)
	v_mfma_f32_16x16x32_bf16 v[52:55], v[140:143], v[112:115], v[52:55]
	v_mfma_f32_16x16x32_bf16 v[48:51], v[140:143], v[120:123], v[48:51]
	ds_read_b64 v[140:141], v230 offset:33856
	ds_read_b64 v[142:143], v230 offset:33888
	s_waitcnt lgkmcnt(10)
	v_mfma_f32_16x16x32_bf16 v[44:47], v[204:207], v[116:119], v[44:47]
	v_mfma_f32_16x16x32_bf16 v[40:43], v[204:207], v[124:127], v[40:43]
	ds_read_b64 v[204:205], v230 offset:36096
	ds_read_b64 v[206:207], v230 offset:36128
	s_waitcnt lgkmcnt(10)
	v_mfma_f32_16x16x32_bf16 v[44:47], v[208:211], v[112:115], v[44:47]
	v_mfma_f32_16x16x32_bf16 v[40:43], v[208:211], v[120:123], v[40:43]
	ds_read_b64 v[208:209], v230 offset:36160
	ds_read_b64 v[210:211], v230 offset:36192
	s_waitcnt lgkmcnt(10)
	v_mfma_f32_16x16x32_bf16 v[36:39], v[128:131], v[116:119], v[36:39]
	v_mfma_f32_16x16x32_bf16 v[28:31], v[128:131], v[124:127], v[28:31]
	ds_read_b64 v[128:129], v230 offset:38400
	ds_read_b64 v[130:131], v230 offset:38432
	s_waitcnt lgkmcnt(10)
	v_mfma_f32_16x16x32_bf16 v[36:39], v[132:135], v[112:115], v[36:39]
	v_mfma_f32_16x16x32_bf16 v[28:31], v[132:135], v[120:123], v[28:31]
	ds_read_b64 v[132:133], v230 offset:38464
	ds_read_b64 v[134:135], v230 offset:38496
	s_waitcnt lgkmcnt(10)
	v_mfma_f32_16x16x32_bf16 v[24:27], v[136:139], v[116:119], v[24:27]
	v_mfma_f32_16x16x32_bf16 v[32:35], v[136:139], v[124:127], v[32:35]
	ds_read_b64 v[136:137], v230 offset:40704
	ds_read_b64 v[138:139], v230 offset:40736
	s_waitcnt lgkmcnt(10)
	v_mfma_f32_16x16x32_bf16 v[24:27], v[140:143], v[112:115], v[24:27]
	v_mfma_f32_16x16x32_bf16 v[32:35], v[140:143], v[120:123], v[32:35]
	ds_read_b64 v[140:141], v230 offset:40768
	ds_read_b64 v[142:143], v230 offset:40800
	s_waitcnt lgkmcnt(10)
	v_mfma_f32_16x16x32_bf16 v[16:19], v[204:207], v[116:119], v[16:19]
	v_mfma_f32_16x16x32_bf16 v[20:23], v[204:207], v[124:127], v[20:23]
	s_waitcnt lgkmcnt(8)
	v_mfma_f32_16x16x32_bf16 v[16:19], v[208:211], v[112:115], v[16:19]
	v_mfma_f32_16x16x32_bf16 v[20:23], v[208:211], v[120:123], v[20:23]
	s_waitcnt lgkmcnt(6)
	v_mfma_f32_16x16x32_bf16 v[8:11], v[128:131], v[116:119], v[8:11]
	v_mfma_f32_16x16x32_bf16 v[12:15], v[128:131], v[124:127], v[12:15]
	s_waitcnt lgkmcnt(4)
	v_mfma_f32_16x16x32_bf16 v[8:11], v[132:135], v[112:115], v[8:11]
	v_mfma_f32_16x16x32_bf16 v[12:15], v[132:135], v[120:123], v[12:15]
	s_waitcnt lgkmcnt(2)
	v_mfma_f32_16x16x32_bf16 v[0:3], v[136:139], v[116:119], v[0:3]
	v_mfma_f32_16x16x32_bf16 v[4:7], v[136:139], v[124:127], v[4:7]
	s_waitcnt lgkmcnt(0)
	v_mfma_f32_16x16x32_bf16 v[0:3], v[140:143], v[112:115], v[0:3]
	v_mfma_f32_16x16x32_bf16 v[4:7], v[140:143], v[120:123], v[4:7]
	s_setprio 0
	s_add_i32 s13, s13, 64
	s_add_i32 s27, s27, 64
	v_readfirstlane_b32 s30, v190
	s_cmp_lt_u32 s30, 0x100
	s_cbranch_scc0 .Lat_eY
	s_waitcnt vmcnt(2) lgkmcnt(0)
	s_barrier
	s_cmp_eq_u32 s26, s28
	s_cbranch_scc0 .Lat_next
	s_waitcnt vmcnt(0)
	s_barrier
	s_branch .LBB0_1011
.Lat_eY:
	s_cmp_eq_u32 s26, s28
	s_cbranch_scc1 .Lat_eYlast
	s_waitcnt vmcnt(3) lgkmcnt(0)
	s_barrier
	s_branch .Lat_next
.Lat_eYlast:
	s_waitcnt vmcnt(0) lgkmcnt(0)
	s_barrier
	s_branch .LBB0_1011
.Lat_next:
	s_mov_b32 s29, s28
	s_branch .LBB0_999
